# placement: pool_in K-loop head padded to address residue 92 mod 128 (on hand-written P0 + S2)
# speedup vs baseline: 1.0019x; 1.0019x over previous
; template <class Epi, class Sched, bool ALIGN_EPI = false, bool SP2 = false>
; __device__ __forceinline__ void gemm_phase(PG8_LAS unsigned char* lds, const Gemm g, const Sched& S, const Epi& E) {
;     ...
;         const bool has_next = S.next(ui + 1, nxt);
;         const char* nA = has_next ? PG8_ABASE(nxt) : cA; const char* nB = has_next ? (const char*)g.Bt + (size_t)nxt.pn * tstepB : cB;
;         for (int t = 0; t < nt; t += 2) {
;             const bool last = (t == nt - 2);
;             if constexpr (Epi::KHOOK) {
;                 if (t == 2) E.fill(cur);
;                 if (t > 0 && (t & 15) == 0) E.khook(acc, (t >> 4) - 1, wr, fr);
;             }
;             const char* a1 = cA + (size_t)(t + 1) * kstep;
;             const char* a2 = last ? nA : cA + (size_t)(t + 2) * kstep; const char* b2 = last ? nB : cB + (size_t)(t + 2) * kstep;
;             const char* a3 = a2 + kstep; const char* b3 = b2 + kstep;
;     ...
;         for (int a = 0; a < 2; ++a)
; #pragma unroll
;             for (int b = 0; b < 2; ++b)
; #pragma unroll
;                 for (int m = 0; m < 4; ++m)
; #pragma unroll
;                     for (int n = 0; n < 2; ++n) acc[a][b][m][n] = (f32x4){0.f, 0.f, 0.f, 0.f};
.LBB0_740:
	s_ashr_i32 s27, s26, 31
	s_lshl_b64 s[28:29], s[26:27], 21
	s_add_u32 s28, s44, s28
	s_addc_u32 s29, s45, s29
	s_and_b64 s[30:31], s[2:3], exec
	s_cselect_b32 s27, s29, s39
	s_cselect_b32 s63, s28, s38
	s_ashr_i32 s25, s24, 31
	s_lshl_b64 s[30:31], s[24:25], 21
	s_add_u32 s30, s46, s30
	s_addc_u32 s31, s47, s31
	s_and_b64 s[42:43], s[2:3], exec
	s_cselect_b32 s25, s31, s41
	s_cselect_b32 s64, s30, s40
	s_add_u32 s38, s38, 0x100080
	s_addc_u32 s39, s39, 0
	s_add_u32 s65, s40, 0x100
	v_mov_b32_e32 v2, 0
	s_addc_u32 s66, s41, 0
	s_mov_b32 s67, -2
	v_mov_b32_e32 v3, v2
	v_mov_b32_e32 v4, v2
	v_mov_b32_e32 v5, v2
	v_mov_b32_e32 v6, v2
	v_mov_b32_e32 v7, v2
	v_mov_b32_e32 v8, v2
	v_mov_b32_e32 v9, v2
	v_mov_b32_e32 v14, v2
	v_mov_b32_e32 v15, v2
	v_mov_b32_e32 v16, v2
	v_mov_b32_e32 v17, v2
	v_mov_b32_e32 v22, v2
	v_mov_b32_e32 v23, v2
	v_mov_b32_e32 v24, v2
	v_mov_b32_e32 v25, v2
	v_mov_b32_e32 v30, v2
	v_mov_b32_e32 v31, v2
	v_mov_b32_e32 v32, v2
	v_mov_b32_e32 v33, v2
	v_mov_b32_e32 v38, v2
	v_mov_b32_e32 v39, v2
	v_mov_b32_e32 v40, v2
	v_mov_b32_e32 v41, v2
	v_mov_b32_e32 v46, v2
	v_mov_b32_e32 v47, v2
	v_mov_b32_e32 v48, v2
	v_mov_b32_e32 v49, v2
	v_mov_b32_e32 v54, v2
	v_mov_b32_e32 v55, v2
	v_mov_b32_e32 v56, v2
	v_mov_b32_e32 v57, v2
	v_mov_b32_e32 v10, v2
	v_mov_b32_e32 v11, v2
	v_mov_b32_e32 v12, v2
	v_mov_b32_e32 v13, v2
	v_mov_b32_e32 v18, v2
	v_mov_b32_e32 v19, v2
	v_mov_b32_e32 v20, v2
	v_mov_b32_e32 v21, v2
	v_mov_b32_e32 v26, v2
	v_mov_b32_e32 v27, v2
	v_mov_b32_e32 v28, v2
	v_mov_b32_e32 v29, v2
	v_mov_b32_e32 v34, v2
	v_mov_b32_e32 v35, v2
	v_mov_b32_e32 v36, v2
	v_mov_b32_e32 v37, v2
	v_mov_b32_e32 v42, v2
	v_mov_b32_e32 v43, v2
	v_mov_b32_e32 v44, v2
	v_mov_b32_e32 v45, v2
	v_mov_b32_e32 v50, v2
	v_mov_b32_e32 v51, v2
	v_mov_b32_e32 v52, v2
	v_mov_b32_e32 v53, v2
	v_mov_b32_e32 v58, v2
	v_mov_b32_e32 v59, v2
	v_mov_b32_e32 v60, v2
	v_mov_b32_e32 v61, v2
	v_mov_b32_e32 v62, v2
	v_mov_b32_e32 v63, v2
	v_mov_b32_e32 v64, v2
	v_mov_b32_e32 v65, v2
	v_mov_b32_e32 v66, v2
	v_mov_b32_e32 v67, v2
	v_mov_b32_e32 v68, v2
	v_mov_b32_e32 v69, v2
	v_mov_b32_e32 v70, v2
	v_mov_b32_e32 v71, v2
	v_mov_b32_e32 v72, v2
	v_mov_b32_e32 v73, v2
	v_mov_b32_e32 v82, v2
	v_mov_b32_e32 v83, v2
	v_mov_b32_e32 v84, v2
	v_mov_b32_e32 v85, v2
	v_mov_b32_e32 v86, v2
	v_mov_b32_e32 v87, v2
	v_mov_b32_e32 v88, v2
	v_mov_b32_e32 v89, v2
	v_mov_b32_e32 v98, v2
	v_mov_b32_e32 v99, v2
	v_mov_b32_e32 v100, v2
	v_mov_b32_e32 v101, v2
	v_mov_b32_e32 v102, v2
	v_mov_b32_e32 v103, v2
	v_mov_b32_e32 v104, v2
	v_mov_b32_e32 v105, v2
	v_mov_b32_e32 v114, v2
	v_mov_b32_e32 v115, v2
	v_mov_b32_e32 v116, v2
	v_mov_b32_e32 v117, v2
	v_mov_b32_e32 v118, v2
	v_mov_b32_e32 v119, v2
	v_mov_b32_e32 v120, v2
	v_mov_b32_e32 v121, v2
	v_mov_b32_e32 v74, v2
	v_mov_b32_e32 v75, v2
	v_mov_b32_e32 v76, v2
	v_mov_b32_e32 v77, v2
	v_mov_b32_e32 v78, v2
	v_mov_b32_e32 v79, v2
	v_mov_b32_e32 v80, v2
	v_mov_b32_e32 v81, v2
	v_mov_b32_e32 v90, v2
	v_mov_b32_e32 v91, v2
	v_mov_b32_e32 v92, v2
	v_mov_b32_e32 v93, v2
	v_mov_b32_e32 v94, v2
	v_mov_b32_e32 v95, v2
	v_mov_b32_e32 v96, v2
	v_mov_b32_e32 v97, v2
	v_mov_b32_e32 v106, v2
	v_mov_b32_e32 v107, v2
	v_mov_b32_e32 v108, v2
	v_mov_b32_e32 v109, v2
	v_mov_b32_e32 v110, v2
	v_mov_b32_e32 v111, v2
	v_mov_b32_e32 v112, v2
	v_mov_b32_e32 v113, v2
	v_mov_b32_e32 v122, v2
	v_mov_b32_e32 v123, v2
	v_mov_b32_e32 v124, v2
	v_mov_b32_e32 v125, v2
	v_mov_b32_e32 v126, v2
	v_mov_b32_e32 v127, v2
	v_mov_b32_e32 v128, v2
	v_mov_b32_e32 v129, v2
	s_nop 0
	s_nop 0
	s_nop 0
	s_nop 0
	s_nop 0
	s_nop 0
	s_nop 0
	s_nop 0
	s_nop 0

; #define PG8_WAIT_V(n) asm volatile("s_waitcnt vmcnt(" #n ")" ::: "memory")
; #define PG8_BAR __builtin_amdgcn_s_barrier()
; template <class Epi, class Sched, bool ALIGN_EPI = false, bool SP2 = false>
; __device__ __forceinline__ void gemm_phase(PG8_LAS unsigned char* lds, const Gemm g, const Sched& S, const Epi& E) {
;     ...
;     PG8_WAIT_V(0);
;     if constexpr (!ALIGN_EPI) { if (wr == 0) PG8_BAR; }
;     PG8_BAR;
.LBB0_751:
	s_waitcnt vmcnt(0)
	s_barrier
	s_nop 0
	s_nop 0
	s_nop 0
	s_nop 0
	s_nop 0
	s_nop 0
	s_nop 0
	s_nop 0
	s_nop 0
	s_nop 0
	s_nop 0
	s_nop 0
	s_nop 0
	s_nop 0
	s_nop 0
	s_nop 0
	s_nop 0
	s_nop 0
	s_nop 0
	s_nop 0
	s_nop 0
	s_nop 0
	s_nop 0
	s_nop 0
	s_nop 0
	s_nop 0
	s_nop 0
	s_nop 0
	s_nop 0
	s_nop 0
	s_nop 0
	s_nop 0
	s_nop 0
	s_nop 0
	s_nop 0
	s_nop 0
	s_nop 0
	s_nop 0
	s_nop 0
	s_nop 0
	s_nop 0
	s_nop 0
	s_nop 0
	s_nop 0
	s_nop 0
	s_nop 0
	s_nop 0
	s_nop 0
	s_nop 0
	s_nop 0
	s_nop 0
	s_nop 0
	s_nop 0
	s_nop 0
	s_nop 0
